# grid-barrier wait: idle waves read the kernel code so next-phase instruction lines are L2-resident; on top of peel+fill
# baseline (speedup 1.0000x reference)
; DI unsigned xb_ld(unsigned* p)              { return __hip_atomic_load(p, __ATOMIC_RELAXED, __HIP_MEMORY_SCOPE_AGENT); }
; #define XB_SPIN(cond, bar) do { unsigned _sp = 0; while (cond) { __builtin_amdgcn_s_sleep(1); \
;     if ((++_sp & 255u) == 0u) { if (xb_ld(&(bar)[XB_TMO])) break; if (_sp > XB_SPIN_CAP) { atomicAdd(&(bar)[XB_TMO], 1u); break; } } } } while (0)
; DI void xcd_barrier(unsigned* bar, volatile LAS unsigned* st) {
;     ...
;             XB_SPIN(xb_ld(&bar[XB_XGEN(x)]) == gen, bar);
;             __builtin_amdgcn_fence(__ATOMIC_ACQUIRE, "agent");
;             asm volatile("s_waitcnt vmcnt(0)" ::: "memory");
;         }
;     }
;     __syncthreads();
.LBB0_892:
	s_or_b64 exec, exec, s[12:13]
	s_waitcnt vmcnt(0)
	s_branch .LBB0_893
.Lwarm:
	s_mov_b64 exec, s[6:7]
	s_getpc_b64 s[0:1]
.Lwarm_here:
	s_add_u32 s0, s0, _Z4mega6Params-.Lwarm_here
	s_addc_u32 s1, s1, -1
	v_subrev_u32_e32 v100, 64, v202
	v_lshlrev_b32_e32 v100, 4, v100
	v_mov_b32_e32 v101, v100
	v_min_u32_e32 v101, 0x1b654, v101
	global_load_dwordx4 v[104:107], v101, s[0:1]
	v_add_u32_e32 v101, 0x1c00, v100
	v_min_u32_e32 v101, 0x1b654, v101
	global_load_dwordx4 v[104:107], v101, s[0:1]
	v_add_u32_e32 v101, 0x3800, v100
	v_min_u32_e32 v101, 0x1b654, v101
	global_load_dwordx4 v[104:107], v101, s[0:1]
	v_add_u32_e32 v101, 0x5400, v100
	v_min_u32_e32 v101, 0x1b654, v101
	global_load_dwordx4 v[104:107], v101, s[0:1]
	v_add_u32_e32 v101, 0x7000, v100
	v_min_u32_e32 v101, 0x1b654, v101
	global_load_dwordx4 v[104:107], v101, s[0:1]
	v_add_u32_e32 v101, 0x8c00, v100
	v_min_u32_e32 v101, 0x1b654, v101
	global_load_dwordx4 v[104:107], v101, s[0:1]
	v_add_u32_e32 v101, 0xa800, v100
	v_min_u32_e32 v101, 0x1b654, v101
	global_load_dwordx4 v[104:107], v101, s[0:1]
	v_add_u32_e32 v101, 0xc400, v100
	v_min_u32_e32 v101, 0x1b654, v101
	global_load_dwordx4 v[104:107], v101, s[0:1]
	v_add_u32_e32 v101, 0xe000, v100
	v_min_u32_e32 v101, 0x1b654, v101
	global_load_dwordx4 v[104:107], v101, s[0:1]
	v_add_u32_e32 v101, 0xfc00, v100
	v_min_u32_e32 v101, 0x1b654, v101
	global_load_dwordx4 v[104:107], v101, s[0:1]
	v_add_u32_e32 v101, 0x11800, v100
	v_min_u32_e32 v101, 0x1b654, v101
	global_load_dwordx4 v[104:107], v101, s[0:1]
	v_add_u32_e32 v101, 0x13400, v100
	v_min_u32_e32 v101, 0x1b654, v101
	global_load_dwordx4 v[104:107], v101, s[0:1]
	v_add_u32_e32 v101, 0x15000, v100
	v_min_u32_e32 v101, 0x1b654, v101
	global_load_dwordx4 v[104:107], v101, s[0:1]
	v_add_u32_e32 v101, 0x16c00, v100
	v_min_u32_e32 v101, 0x1b654, v101
	global_load_dwordx4 v[104:107], v101, s[0:1]
	v_add_u32_e32 v101, 0x18800, v100
	v_min_u32_e32 v101, 0x1b654, v101
	global_load_dwordx4 v[104:107], v101, s[0:1]
	v_add_u32_e32 v101, 0x1a400, v100
	v_min_u32_e32 v101, 0x1b654, v101
	global_load_dwordx4 v[104:107], v101, s[0:1]
	s_waitcnt vmcnt(0)
